# v54 + one static priority raise for waves 4-7 during the attention phase (re-test under the one-barrier-per-iteration loop)
# speedup vs baseline: 1.0052x; 1.0052x over previous
; __device__ __forceinline__ int opaque_tid() { int t = threadIdx.x; asm volatile("" : "+v"(t)); return t; }
; __device__ __forceinline__ u32x4 pack8(f32x4 a, f32x4 b) { u32x4 w; w.x = cvt_pk_bf16(a[0], a[1]); w.y = cvt_pk_bf16(a[2], a[3]); w.z = cvt_pk_bf16(b[0], b[1]); w.w = cvt_pk_bf16(b[2], b[3]); return w; }
; __device__ __forceinline__ bf16x8 pack8(f32x4 a, f32x4 b) { u32x4 w = {cvtpk(a[0], a[1]), cvtpk(a[2], a[3]), cvtpk(b[0], b[1]), cvtpk(b[2], b[3])}; return *reinterpret_cast<bf16x8*>(&w); }
; #define VMW() asm volatile("s_waitcnt vmcnt(0)" ::: "memory")
; #define SLOAD_H(Kp, Vp, k0) do { S.st_v0 = load8(ROW(Vp, k0, sr)); S.st_v1 = load8(ROW(Vp, k0, 32 + sr));              \
;                          S.st_k0 = load8(ROW(Kp, k0, sr)); S.st_k1 = load8(ROW(Kp, k0, 32 + sr)); } while (0)
; #define SWRITE_HK(bf) do { *(bf16x8*)(K_lds + (bf) * SHM_K + kws) = S.st_k0; *(bf16x8*)(K_lds + (bf) * SHM_K + kws + 32 * 256) = S.st_k1; } while (0)
; __device__ __forceinline__ void stage_kmean(char* lds, const float* km) {
;     const int tid = opaque_tid(), row = tid >> 4, chunk = tid & 15;
;     const float* kp = km + (row & 15) * 128 + chunk * 8;
;     f32x4 a = *(const f32x4*)kp, b = *(const f32x4*)(kp + 4);
;     a = a * (1.0f / 256.0f); b = b * (1.0f / 256.0f);
;     const bf16x8 h = pack8(a, b);
;     f32x4 ah, bh;
; #pragma unroll
;     for (int j = 0; j < 4; ++j) { ah[j] = __uint_as_float(((unsigned)(unsigned short)h[j]) << 16); bh[j] = __uint_as_float(((unsigned)(unsigned short)h[4 + j]) << 16); }
;     const bf16x8 l = pack8(a - ah, b - bh);
;     *(bf16x8*)(lds + KM_LDS_OFF + row * KM_PITCH + chunk * 16) = (row >= 16) ? l : h;
; }
; __device__ __forceinline__ void moba_prime(const BlockRef& cur, char* lds, Seam& S) {
;     const int tid = opaque_tid(), wid = __builtin_amdgcn_readfirstlane(tid >> 6), lane = tid & 63, r32 = lane & 31, hi = lane >> 5;
;     const int sr = tid >> 4, sc = (tid & 15) * 8, kws = KSWZ(sr, sc * 2); char* K_lds = lds + 2 * SHM_V;
;     for (int d0 = 0; d0 < 8; ++d0) S.qr[d0] = load8(cur.Q + (size_t)(wid * QBLK + r32) * D + d0 * 16 + hi * 8);
;     SLOAD_H(cur.K, cur.V, 0); VMW(); SWRITE_HK(0);
;     __syncthreads();
; }
.LBB0_75:
.LBB0_76:
	v_readlane_b32 s0, v254, 4
	v_readlane_b32 s1, v254, 5
	s_andn2_b64 vcc, exec, s[0:1]
	s_cbranch_vccnz .LBB0_247
	v_readfirstlane_b32 s100, v0
	s_cmp_ge_u32 s100, 0x100
	s_cbranch_scc0 .Lmy_prio_skip
	s_setprio 1
.Lmy_prio_skip:
	s_and_b64 s[0:1], s[72:73], exec
	s_cselect_b32 s0, 0x40000, 0
	v_readlane_b32 s2, v253, 37
	v_readlane_b32 s3, v253, 38
	s_add_u32 s45, s2, s0
	s_waitcnt vmcnt(0)
	v_mov_b32_e32 v2, v0
	s_addc_u32 s79, s3, 0
	v_readlane_b32 s0, v254, 0
	v_readlane_b32 s1, v254, 1
	v_ashrrev_i32_e32 v18, 4, v2
	s_add_u32 s18, s45, s0
	v_and_b32_e32 v19, 15, v2
	v_lshlrev_b32_e32 v2, 9, v18
	s_addc_u32 s19, s79, s1
	v_and_b32_e32 v98, 0x1e00, v2
	s_waitcnt lgkmcnt(0)
	v_lshl_add_u64 v[2:3], s[18:19], 0, v[98:99]
	v_lshlrev_b32_e32 v98, 5, v19
	v_lshl_add_u64 v[6:7], v[2:3], 0, v[98:99]
	global_load_dwordx4 v[2:5], v[6:7], off offset:16
	s_nop 0
	global_load_dwordx4 v[6:9], v[6:7], off
	s_mov_b32 s0, 0x3b800000
	v_cmp_lt_i32_e32 vcc, 15, v18
	v_readlane_b32 s14, v253, 49
	v_readlane_b32 s15, v253, 50
	v_readlane_b32 s22, v253, 57
	v_readlane_b32 s23, v253, 58
	v_readlane_b32 s30, v253, 53
	v_readlane_b32 s31, v253, 54
	s_mov_b64 s[46:47], s[92:93]
	v_readlane_b32 s92, v253, 62
	v_readlane_b32 s44, v253, 59
	v_readlane_b32 s2, v253, 48
	v_readlane_b32 s93, v253, 63
	s_mov_b64 s[10:11], -1
	s_mov_b32 s85, s90
	s_mov_b32 s86, s44
	s_mov_b32 s89, s2
	s_mov_b64 s[4:5], s[92:93]
	s_mov_b64 s[16:17], s[22:23]
	s_mov_b64 s[28:29], s[30:31]
	s_waitcnt vmcnt(1)
	v_pk_mul_f32 v[14:15], v[4:5], s[0:1] op_sel_hi:[1,0]
	s_waitcnt vmcnt(0)
	v_pk_mul_f32 v[10:11], v[8:9], s[0:1] op_sel_hi:[1,0]
	s_waitcnt lgkmcnt(0)
	v_pk_mul_f32 v[12:13], v[6:7], s[0:1] op_sel_hi:[1,0]
	v_pk_mul_f32 v[16:17], v[2:3], s[0:1] op_sel_hi:[1,0]
	v_cvt_pk_bf16_f32 v12, v12, v13
	v_cvt_pk_bf16_f32 v13, v10, v11
	s_nop 0
	v_lshlrev_b32_e32 v10, 16, v13
	v_and_b32_e32 v11, 0xffff0000, v13
	v_lshlrev_b32_e32 v21, 16, v12
	v_and_b32_e32 v22, 0xffff0000, v12
	v_xor_b32_e32 v11, 0x80000000, v11
	v_xor_b32_e32 v10, 0x80000000, v10
	v_cvt_pk_bf16_f32 v16, v16, v17
	v_cvt_pk_bf16_f32 v14, v14, v15
	v_pk_fma_f32 v[8:9], v[8:9], s[0:1], v[10:11] op_sel_hi:[1,0,1]
	v_lshlrev_b32_e32 v20, 16, v14
	v_and_b32_e32 v23, 0xffff0000, v14
	v_xor_b32_e32 v11, 0x80000000, v22
	v_xor_b32_e32 v10, 0x80000000, v21
	v_lshlrev_b32_e32 v15, 16, v16
	v_and_b32_e32 v17, 0xffff0000, v16
	v_pk_fma_f32 v[6:7], v[6:7], s[0:1], v[10:11] op_sel_hi:[1,0,1]
	v_xor_b32_e32 v11, 0x80000000, v23
	v_xor_b32_e32 v10, 0x80000000, v20
	v_pk_fma_f32 v[4:5], v[4:5], s[0:1], v[10:11] op_sel_hi:[1,0,1]
	v_xor_b32_e32 v11, 0x80000000, v17
	v_xor_b32_e32 v10, 0x80000000, v15
	v_pk_fma_f32 v[2:3], v[2:3], s[0:1], v[10:11] op_sel_hi:[1,0,1]
	v_cvt_pk_bf16_f32 v6, v6, v7
	v_cvt_pk_bf16_f32 v7, v8, v9
	s_movk_i32 s0, 0x110
	v_cvt_pk_bf16_f32 v8, v2, v3
	v_cvt_pk_bf16_f32 v2, v4, v5
	v_cndmask_b32_e32 v3, v13, v7, vcc
	v_cndmask_b32_e32 v5, v14, v2, vcc
	v_cndmask_b32_e32 v2, v12, v6, vcc
	v_mul_lo_u32 v6, v18, s0
	v_lshlrev_b32_e32 v7, 4, v19
	v_readlane_b32 s0, v255, 35
	v_cndmask_b32_e32 v4, v16, v8, vcc
	s_nop 0
	v_add3_u32 v6, s0, v6, v7
	ds_write_b128 v6, v[2:5]
	v_mov_b32_e32 v4, v0
	s_nop 0
	v_readfirstlane_b32 s0, v4
	s_ashr_i32 s0, s0, 1
	v_lshrrev_b32_e32 v5, 1, v4
	v_mov_b32_e32 v2, s0
	s_movk_i32 s0, 0xffe0
	v_bfi_b32 v2, s0, v2, v4
	v_ashrrev_i32_e32 v3, 31, v2
	v_lshlrev_b64 v[2:3], 8, v[2:3]
	v_lshl_add_u64 v[2:3], s[14:15], 0, v[2:3]
	v_and_b32_e32 v98, 16, v5
	v_lshl_add_u64 v[2:3], v[2:3], 0, v[98:99]
	global_load_dwordx4 v[132:135], v[2:3], off
	global_load_dwordx4 v[128:131], v[2:3], off offset:32
	global_load_dwordx4 v[124:127], v[2:3], off offset:64
	global_load_dwordx4 v[120:123], v[2:3], off offset:96
	global_load_dwordx4 v[116:119], v[2:3], off offset:128
	global_load_dwordx4 v[112:115], v[2:3], off offset:160
	global_load_dwordx4 v[108:111], v[2:3], off offset:192
	global_load_dwordx4 v[104:107], v[2:3], off offset:224
	v_ashrrev_i32_e32 v2, 4, v4
	v_lshlrev_b32_e32 v3, 4, v4
	v_and_b32_e32 v4, 0x70, v4
	s_movk_i32 s0, 0xf0
	v_and_b32_e32 v98, 0xf0, v3
	v_bitop3_b32 v11, v3, v4, s0 bitop3:0x6c
	v_ashrrev_i32_e32 v3, 31, v2
	v_lshlrev_b32_e32 v10, 8, v2
	v_lshlrev_b64 v[2:3], 8, v[2:3]
	v_lshl_add_u64 v[4:5], s[22:23], 0, v[2:3]
	s_mov_b64 s[0:1], 0x2000
	v_lshl_add_u64 v[4:5], v[4:5], 0, v[98:99]
	v_lshl_add_u64 v[6:7], v[2:3], 0, s[0:1]
	global_load_dwordx4 v[100:103], v[4:5], off
	v_lshl_add_u64 v[4:5], s[22:23], 0, v[6:7]
	v_lshl_add_u64 v[2:3], s[30:31], 0, v[2:3]
	v_lshl_add_u64 v[4:5], v[4:5], 0, v[98:99]
	v_lshl_add_u64 v[2:3], v[2:3], 0, v[98:99]
	v_lshl_add_u64 v[6:7], s[30:31], 0, v[6:7]
	global_load_dwordx4 v[136:139], v[4:5], off
	v_lshl_add_u64 v[6:7], v[6:7], 0, v[98:99]
	global_load_dwordx4 v[2:5], v[2:3], off
	v_add3_u32 v10, 0, v10, v11
	global_load_dwordx4 v[6:9], v[6:7], off
	s_waitcnt vmcnt(0)
	s_waitcnt vmcnt(1)
	ds_write_b128 v10, v[2:5] offset:32768
	s_waitcnt vmcnt(0)
	ds_write_b128 v10, v[6:9] offset:40960
	s_waitcnt lgkmcnt(0)
	s_barrier
	s_branch .LBB0_80

; __global__ void __launch_bounds__(NWAVES * 64, 2) trunk_fwd(Args args) {
;     ...
;                 if (kind == 0) { if (PM & 32) att::moba_phase((char*)lds_raw, ACT0, ACT1, ACT2, ACT3, (const float*)(ws + WS_KM) + (size_t)li * 65536, vcu, G); }
;                 else if (PM & 64) conv_prep(ACT0, ACT1, args.in[9], ACT2, vcu, G, tid);
;             }
;         }
;         if (ph + 1 < args.ph_hi) xcd_barrier(bar);
.LBB0_246:
	s_setprio 0
	v_readlane_b32 s88, v255, 45
	v_readlane_b32 s90, v255, 40
	s_mov_b64 s[92:93], s[46:47]
	v_readlane_b32 s89, v255, 46
	v_readlane_b32 s85, v255, 47
	s_mov_b32 s29, 0x1ffff
